# nt (non-temporal) hint on the once-read f32 weight loads of the bf16 weight conversion, to keep them from displacing activations in L2/MALL
# speedup vs baseline: 1.0053x; 1.0053x over previous
; #define LAS __attribute__((address_space(3)))
; __device__ __forceinline__ unsigned pk2(float lo, float hi) { f32x2_t v = {lo, hi}; bf16x2_t b = __builtin_convertvector(v, bf16x2_t); return __builtin_bit_cast(unsigned, b); }
; #define LDS_WAIT() asm volatile("s_waitcnt lgkmcnt(0)" ::: "memory")
; template <int MAP>
; __device__ __forceinline__ void transpose_item(const float* W, int K, int N, bf16_t* WT, int ldk, LAS float* scr, int item, int nblk, int lane) {
;     const int kb = item / nblk, nb = item % nblk, k0 = 64 * kb, n0 = 32 * nb;
;     const int cc = n0 + 4 * (lane & 7);
; #pragma unroll
;     for (int i = 0; i < 8; ++i) { const int kk = 8 * i + (lane >> 3); f32x4 v = {0.f, 0.f, 0.f, 0.f}; if (cc < N) v = *(const f32x4*)(W + (size_t)(k0 + kk) * N + cc);
;         LAS float* d = scr + kk * 33 + 4 * (lane & 7); d[0] = v.x; d[1] = v.y; d[2] = v.z; d[3] = v.w; }
;     LDS_WAIT();
;     const int c = lane & 7;
; #pragma unroll
;     for (int j = 0; j < 4; ++j) { const int n = (lane >> 3) + 8 * j; const LAS float* s = scr + (8 * c) * 33 + n;
;         u32x4 o; o.x = pk2(s[0 * 33], s[1 * 33]); o.y = pk2(s[2 * 33], s[3 * 33]); o.z = pk2(s[4 * 33], s[5 * 33]); o.w = pk2(s[6 * 33], s[7 * 33]);
;         const int dr = MAP ? swiglu_row(n0 + n) : (n0 + n);
;         *(u32x4*)(WT + (size_t)dr * ldk + k0 + 8 * c) = o; }
;     LDS_WAIT();
; }
.LBB0_93:
	s_andn2_b64 vcc, exec, s[4:5]
	v_add_u32_e32 v41, 0x420, v28
	v_add_u32_e32 v42, 0x428, v28
	v_add_u32_e32 v37, 0x840, v28
	v_add_u32_e32 v38, 0x848, v28
	v_add_u32_e32 v39, 0xc60, v28
	v_add_u32_e32 v40, 0xc68, v28
	v_add_u32_e32 v33, 0x1080, v28
	v_add_u32_e32 v34, 0x1088, v28
	v_add_u32_e32 v35, 0x14a0, v28
	v_add_u32_e32 v36, 0x14a8, v28
	v_add_u32_e32 v29, 0x18c0, v28
	v_add_u32_e32 v30, 0x18c8, v28
	v_add_u32_e32 v31, 0x1ce0, v28
	v_add_u32_e32 v32, 0x1ce8, v28
	s_cbranch_vccnz .LBB0_111
	v_readlane_b32 s0, v254, 36
	v_readlane_b32 s1, v254, 37
	s_load_dwordx2 s[0:1], s[0:1], 0x10
	s_mul_hi_i32 s4, s16, 0x2e8ba2e9
	s_movk_i32 s7, 0x5800
	s_waitcnt lgkmcnt(0)
	s_add_u32 s0, s0, s10
	s_addc_u32 s1, s1, s9
	s_lshr_b32 s5, s4, 31
	s_ashr_i32 s4, s4, 5
	s_add_i32 s5, s4, s5
	s_mul_i32 s6, s5, 0xffffea00
	s_add_i32 s6, s6, s13
	v_add_u32_e32 v2, s6, v18
	s_lshl_b32 s4, s5, 6
	v_ashrrev_i32_e32 v3, 31, v2
	v_lshl_add_u64 v[6:7], v[2:3], 2, s[0:1]
	v_add_u32_e32 v2, s4, v19
	v_mad_i64_i32 v[2:3], s[0:1], v2, s7, v[6:7]
	global_load_dwordx4 v[200:203], v[2:3], off nt
	v_add_u32_e32 v44, s6, v19
	s_mulk_i32 s5, 0xd400
	v_cmp_lt_i32_e32 vcc, s51, v44
	v_add_u32_e32 v43, s5, v27
	v_add_u32_e32 v2, s4, v20
	v_mad_i64_i32 v[2:3], s[0:1], v2, s7, v[6:7]
	global_load_dwordx4 v[204:207], v[2:3], off nt
	v_add_u32_e32 v2, s4, v21
	v_mad_i64_i32 v[2:3], s[0:1], v2, s7, v[6:7]
	global_load_dwordx4 v[208:211], v[2:3], off nt
	v_add_u32_e32 v2, s4, v22
	v_mad_i64_i32 v[2:3], s[0:1], v2, s7, v[6:7]
	global_load_dwordx4 v[212:215], v[2:3], off nt
	v_add_u32_e32 v2, s4, v23
	v_mad_i64_i32 v[2:3], s[0:1], v2, s7, v[6:7]
	global_load_dwordx4 v[216:219], v[2:3], off nt
	v_add_u32_e32 v2, s4, v24
	v_mad_i64_i32 v[2:3], s[0:1], v2, s7, v[6:7]
	global_load_dwordx4 v[220:223], v[2:3], off nt
	v_add_u32_e32 v2, s4, v25
	v_mad_i64_i32 v[2:3], s[0:1], v2, s7, v[6:7]
	global_load_dwordx4 v[224:227], v[2:3], off nt
	v_add_u32_e32 v2, s4, v26
	v_mad_i64_i32 v[2:3], s[0:1], v2, s7, v[6:7]
	global_load_dwordx4 v[228:231], v[2:3], off nt
	s_waitcnt vmcnt(7)
	ds_write2_b32 v28, v200, v201 offset1:1
	ds_write2_b32 v28, v202, v203 offset0:2 offset1:3
	s_waitcnt vmcnt(6)
	ds_write2_b32 v41, v204, v205 offset1:1
	ds_write2_b32 v42, v206, v207 offset1:1
	s_waitcnt vmcnt(5)
	ds_write2_b32 v37, v208, v209 offset1:1
	ds_write2_b32 v38, v210, v211 offset1:1
	s_waitcnt vmcnt(4)
	ds_write2_b32 v39, v212, v213 offset1:1
	ds_write2_b32 v40, v214, v215 offset1:1
	s_waitcnt vmcnt(3)
	ds_write2_b32 v33, v216, v217 offset1:1
	ds_write2_b32 v34, v218, v219 offset1:1
	s_waitcnt vmcnt(2)
	ds_write2_b32 v35, v220, v221 offset1:1
	ds_write2_b32 v36, v222, v223 offset1:1
	s_waitcnt vmcnt(1)
	ds_write2_b32 v29, v224, v225 offset1:1
	ds_write2_b32 v30, v226, v227 offset1:1
	s_waitcnt vmcnt(0)
	ds_write2_b32 v31, v228, v229 offset1:1
	ds_write2_b32 v32, v230, v231 offset1:1
	s_waitcnt lgkmcnt(0)
	ds_read2_b32 v[4:5], v0 offset1:33
	ds_read2_b32 v[6:7], v0 offset0:66 offset1:99
	ds_read2_b32 v[8:9], v0 offset0:132 offset1:165
	ds_read2_b32 v[14:15], v0 offset0:198 offset1:231
	v_and_b32_e32 v2, 0x7f, v44
	s_and_saveexec_b64 s[0:1], vcc
	s_xor_b64 s[6:7], exec, s[0:1]
	v_subrev_u32_e32 v3, 48, v43
	v_and_b32_e32 v3, 0x7fffff00, v3
	v_or3_b32 v16, v2, v3, s54
	s_andn2_saveexec_b64 s[6:7], s[6:7]
	v_add_u32_e32 v3, 0x800015d0, v43
	v_and_or_b32 v16, v3, s55, v2
	s_or_b64 exec, exec, s[6:7]
	s_ashr_i32 s5, s4, 31
	v_ashrrev_i32_e32 v17, 31, v16
	v_lshl_add_u64 v[2:3], s[4:5], 1, v[10:11]
	s_waitcnt lgkmcnt(3)
	v_cvt_pk_bf16_f32 v4, v4, v5
	s_waitcnt lgkmcnt(2)
	v_cvt_pk_bf16_f32 v5, v6, v7
	s_waitcnt lgkmcnt(1)
	v_cvt_pk_bf16_f32 v6, v8, v9
	v_lshlrev_b64 v[8:9], 11, v[16:17]
	s_waitcnt lgkmcnt(0)
	v_cvt_pk_bf16_f32 v7, v14, v15
	v_lshl_add_u64 v[8:9], v[2:3], 0, v[8:9]
	global_store_dwordx4 v[8:9], v[4:7], off
	ds_read2_b32 v[4:5], v0 offset0:8 offset1:41
	ds_read2_b32 v[6:7], v0 offset0:74 offset1:107
	ds_read2_b32 v[8:9], v0 offset0:140 offset1:173
	ds_read2_b32 v[14:15], v0 offset0:206 offset1:239
	v_add_u32_e32 v16, 8, v44
	v_cmp_lt_i32_e32 vcc, s51, v16
	v_and_b32_e32 v17, 0x7f, v16
	s_and_saveexec_b64 s[0:1], vcc
	s_xor_b64 s[4:5], exec, s[0:1]
	v_subrev_u32_e32 v16, 32, v43
	v_and_b32_e32 v16, 0x7fffff00, v16
	v_or3_b32 v16, v17, v16, s54
	s_andn2_saveexec_b64 s[4:5], s[4:5]
	v_add_u32_e32 v16, 0x800015e0, v43
	v_and_or_b32 v16, v16, s55, v17
	s_or_b64 exec, exec, s[4:5]
	v_ashrrev_i32_e32 v17, 31, v16
	s_waitcnt lgkmcnt(3)
	v_cvt_pk_bf16_f32 v4, v4, v5
	s_waitcnt lgkmcnt(2)
	v_cvt_pk_bf16_f32 v5, v6, v7
	s_waitcnt lgkmcnt(1)
	v_cvt_pk_bf16_f32 v6, v8, v9
	v_lshlrev_b64 v[8:9], 11, v[16:17]
	s_waitcnt lgkmcnt(0)
	v_cvt_pk_bf16_f32 v7, v14, v15
	v_lshl_add_u64 v[8:9], v[2:3], 0, v[8:9]
	global_store_dwordx4 v[8:9], v[4:7], off
	ds_read2_b32 v[4:5], v0 offset0:16 offset1:49
	ds_read2_b32 v[6:7], v0 offset0:82 offset1:115
	ds_read2_b32 v[8:9], v0 offset0:148 offset1:181
	ds_read2_b32 v[14:15], v0 offset0:214 offset1:247
	v_add_u32_e32 v16, 16, v44
	v_cmp_lt_i32_e32 vcc, s51, v16
	v_and_b32_e32 v17, 0x7f, v16
	s_and_saveexec_b64 s[0:1], vcc
	s_xor_b64 s[4:5], exec, s[0:1]
	v_add_u32_e32 v16, -16, v43
	v_and_b32_e32 v16, 0x7fffff00, v16
	v_or3_b32 v16, v17, v16, s54
	s_andn2_saveexec_b64 s[4:5], s[4:5]
	v_add_u32_e32 v16, 0x800015f0, v43
	v_and_or_b32 v16, v16, s55, v17
	s_or_b64 exec, exec, s[4:5]
	v_ashrrev_i32_e32 v17, 31, v16
	s_waitcnt lgkmcnt(3)
	v_cvt_pk_bf16_f32 v4, v4, v5
	s_waitcnt lgkmcnt(2)
	v_cvt_pk_bf16_f32 v5, v6, v7
	s_waitcnt lgkmcnt(1)
	v_cvt_pk_bf16_f32 v6, v8, v9
	v_lshlrev_b64 v[8:9], 11, v[16:17]
	s_waitcnt lgkmcnt(0)
	v_cvt_pk_bf16_f32 v7, v14, v15
	v_lshl_add_u64 v[8:9], v[2:3], 0, v[8:9]
	global_store_dwordx4 v[8:9], v[4:7], off
	ds_read2_b32 v[4:5], v0 offset0:24 offset1:57
	ds_read2_b32 v[6:7], v0 offset0:90 offset1:123
	ds_read2_b32 v[8:9], v0 offset0:156 offset1:189
	ds_read2_b32 v[14:15], v0 offset0:222 offset1:255
	v_add_u32_e32 v16, 24, v44
	v_cmp_lt_i32_e32 vcc, s51, v16
	v_and_b32_e32 v17, 0x7f, v16
	s_and_saveexec_b64 s[0:1], vcc
	s_xor_b64 s[4:5], exec, s[0:1]
	v_and_b32_e32 v16, 0x7fffff00, v43
	v_or3_b32 v16, v17, v16, s54
	s_andn2_saveexec_b64 s[4:5], s[4:5]
	v_add_u32_e32 v16, 0x80001600, v43
	v_and_or_b32 v16, v16, s55, v17
	s_or_b64 exec, exec, s[4:5]
	v_ashrrev_i32_e32 v17, 31, v16
	s_waitcnt lgkmcnt(3)
	v_cvt_pk_bf16_f32 v4, v4, v5
	s_waitcnt lgkmcnt(2)
	v_cvt_pk_bf16_f32 v5, v6, v7
	s_waitcnt lgkmcnt(1)
	v_cvt_pk_bf16_f32 v6, v8, v9
	v_lshlrev_b64 v[8:9], 11, v[16:17]
	s_waitcnt lgkmcnt(0)
	v_cvt_pk_bf16_f32 v7, v14, v15
	v_lshl_add_u64 v[2:3], v[2:3], 0, v[8:9]
	global_store_dwordx4 v[2:3], v[4:7], off
	s_waitcnt lgkmcnt(0)
	s_mov_b32 s17, s16

; #define LAS __attribute__((address_space(3)))
; template <int MAP>
; __device__ __forceinline__ void transpose_item(const float* W, int K, int N, bf16_t* WT, int ldk, LAS float* scr, int item, int nblk, int lane) {
;     ...
; #pragma unroll
;     for (int i = 0; i < 8; ++i) { const int kk = 8 * i + (lane >> 3); f32x4 v = {0.f, 0.f, 0.f, 0.f}; if (cc < N) v = *(const f32x4*)(W + (size_t)(k0 + kk) * N + cc);
;         LAS float* d = scr + kk * 33 + 4 * (lane & 7); d[0] = v.x; d[1] = v.y; d[2] = v.z; d[3] = v.w; }
.LBB0_114:
	s_or_saveexec_b64 s[4:5], s[2:3]
	s_lshl_b32 s0, s18, 1
	v_ashrrev_i32_e32 v3, 31, v2
	s_and_b32 s2, s0, 0xffffffc0
	v_lshl_add_u64 v[14:15], v[2:3], 2, s[6:7]
	v_mov_b32_e32 v6, 0
	v_mov_b32_e32 v7, 0
	v_mov_b32_e32 v8, 0
	v_mov_b32_e32 v9, 0
	v_mov_b32_e32 v2, 0
	v_mov_b32_e32 v3, 0
	v_mov_b32_e32 v4, 0
	v_mov_b32_e32 v5, 0
	s_xor_b64 exec, exec, s[4:5]
	s_cbranch_execz .LBB0_116
	v_add_u32_e32 v2, s2, v19
	v_ashrrev_i32_e32 v3, 31, v2
	v_lshlrev_b64 v[2:3], 12, v[2:3]
	v_add_u32_e32 v6, s2, v20
	v_lshl_add_u64 v[2:3], v[14:15], 0, v[2:3]
	v_ashrrev_i32_e32 v7, 31, v6
	global_load_dwordx4 v[2:5], v[2:3], off nt
	v_lshlrev_b64 v[6:7], 12, v[6:7]
	v_lshl_add_u64 v[6:7], v[14:15], 0, v[6:7]
	global_load_dwordx4 v[6:9], v[6:7], off nt
	s_waitcnt vmcnt(1)
	ds_write2_b32 v28, v2, v3 offset1:1
	ds_write2_b32 v28, v4, v5 offset0:2 offset1:3
	s_waitcnt vmcnt(0)
	ds_write2_b32 v41, v6, v7 offset1:1
	ds_write2_b32 v42, v8, v9 offset1:1
	v_add_u32_e32 v2, s2, v21
	v_add_u32_e32 v6, s2, v22
	v_ashrrev_i32_e32 v3, 31, v2
	v_ashrrev_i32_e32 v7, 31, v6
	v_lshlrev_b64 v[2:3], 12, v[2:3]
	v_lshlrev_b64 v[6:7], 12, v[6:7]
	v_lshl_add_u64 v[2:3], v[14:15], 0, v[2:3]
	v_lshl_add_u64 v[6:7], v[14:15], 0, v[6:7]
	global_load_dwordx4 v[2:5], v[2:3], off nt
	s_nop 0
	global_load_dwordx4 v[6:9], v[6:7], off nt

; #define LAS __attribute__((address_space(3)))
; template <int MAP>
; __device__ __forceinline__ void transpose_item(const float* W, int K, int N, bf16_t* WT, int ldk, LAS float* scr, int item, int nblk, int lane) {
;     ...
; #pragma unroll
;     for (int i = 0; i < 8; ++i) { const int kk = 8 * i + (lane >> 3); f32x4 v = {0.f, 0.f, 0.f, 0.f}; if (cc < N) v = *(const f32x4*)(W + (size_t)(k0 + kk) * N + cc);
;         LAS float* d = scr + kk * 33 + 4 * (lane & 7); d[0] = v.x; d[1] = v.y; d[2] = v.z; d[3] = v.w; }
.LBB0_118:
	s_or_saveexec_b64 s[4:5], s[4:5]
	v_mov_b32_e32 v6, 0
	v_mov_b32_e32 v7, 0
	v_mov_b32_e32 v8, 0
	v_mov_b32_e32 v9, 0
	v_mov_b32_e32 v2, 0
	v_mov_b32_e32 v3, 0
	v_mov_b32_e32 v4, 0
	v_mov_b32_e32 v5, 0
	s_xor_b64 exec, exec, s[4:5]
	s_cbranch_execz .LBB0_89
	v_add_u32_e32 v2, s2, v23
	v_ashrrev_i32_e32 v3, 31, v2
	v_lshlrev_b64 v[2:3], 12, v[2:3]
	v_add_u32_e32 v6, s2, v24
	v_lshl_add_u64 v[2:3], v[14:15], 0, v[2:3]
	v_ashrrev_i32_e32 v7, 31, v6
	global_load_dwordx4 v[2:5], v[2:3], off nt
	v_lshlrev_b64 v[6:7], 12, v[6:7]
	v_lshl_add_u64 v[6:7], v[14:15], 0, v[6:7]
	global_load_dwordx4 v[6:9], v[6:7], off nt
	s_waitcnt vmcnt(1)
	ds_write2_b32 v33, v2, v3 offset1:1
	ds_write2_b32 v34, v4, v5 offset1:1
	s_waitcnt vmcnt(0)
	ds_write2_b32 v35, v6, v7 offset1:1
	ds_write2_b32 v36, v8, v9 offset1:1
	v_add_u32_e32 v2, s2, v25
	v_add_u32_e32 v6, s2, v26
	v_ashrrev_i32_e32 v3, 31, v2
	v_ashrrev_i32_e32 v7, 31, v6
	v_lshlrev_b64 v[2:3], 12, v[2:3]
	v_lshlrev_b64 v[6:7], 12, v[6:7]
	v_lshl_add_u64 v[2:3], v[14:15], 0, v[2:3]
	v_lshl_add_u64 v[6:7], v[14:15], 0, v[6:7]
	global_load_dwordx4 v[2:5], v[2:3], off nt
	s_nop 0
	global_load_dwordx4 v[6:9], v[6:7], off nt
	s_branch .LBB0_89

; #define LAS __attribute__((address_space(3)))
; __device__ __forceinline__ unsigned pk2(float lo, float hi) { f32x2_t v = {lo, hi}; bf16x2_t b = __builtin_convertvector(v, bf16x2_t); return __builtin_bit_cast(unsigned, b); }
; #define LDS_WAIT() asm volatile("s_waitcnt lgkmcnt(0)" ::: "memory")
; template <int MAP>
; __device__ __forceinline__ void transpose_item(const float* W, int K, int N, bf16_t* WT, int ldk, LAS float* scr, int item, int nblk, int lane) {
;     const int kb = item / nblk, nb = item % nblk, k0 = 64 * kb, n0 = 32 * nb;
;     const int cc = n0 + 4 * (lane & 7);
; #pragma unroll
;     for (int i = 0; i < 8; ++i) { const int kk = 8 * i + (lane >> 3); f32x4 v = {0.f, 0.f, 0.f, 0.f}; if (cc < N) v = *(const f32x4*)(W + (size_t)(k0 + kk) * N + cc);
;         LAS float* d = scr + kk * 33 + 4 * (lane & 7); d[0] = v.x; d[1] = v.y; d[2] = v.z; d[3] = v.w; }
;     LDS_WAIT();
;     const int c = lane & 7;
; #pragma unroll
;     for (int j = 0; j < 4; ++j) { const int n = (lane >> 3) + 8 * j; const LAS float* s = scr + (8 * c) * 33 + n;
;         u32x4 o; o.x = pk2(s[0 * 33], s[1 * 33]); o.y = pk2(s[2 * 33], s[3 * 33]); o.z = pk2(s[4 * 33], s[5 * 33]); o.w = pk2(s[6 * 33], s[7 * 33]);
;         const int dr = MAP ? swiglu_row(n0 + n) : (n0 + n);
;         *(u32x4*)(WT + (size_t)dr * ldk + k0 + 8 * c) = o; }
;     LDS_WAIT();
; }
.LBB0_128:
	s_andn2_b64 vcc, exec, s[4:5]
	v_add_u32_e32 v41, 0x420, v28
	v_add_u32_e32 v42, 0x428, v28
	v_add_u32_e32 v37, 0x840, v28
	v_add_u32_e32 v38, 0x848, v28
	v_add_u32_e32 v39, 0xc60, v28
	v_add_u32_e32 v40, 0xc68, v28
	v_add_u32_e32 v33, 0x1080, v28
	v_add_u32_e32 v34, 0x1088, v28
	v_add_u32_e32 v35, 0x14a0, v28
	v_add_u32_e32 v36, 0x14a8, v28
	v_add_u32_e32 v29, 0x18c0, v28
	v_add_u32_e32 v30, 0x18c8, v28
	v_add_u32_e32 v31, 0x1ce0, v28
	v_add_u32_e32 v32, 0x1ce8, v28
	s_cbranch_vccnz .LBB0_146
	v_readlane_b32 s0, v254, 36
	v_readlane_b32 s1, v254, 37
	s_load_dwordx2 s[0:1], s[0:1], 0xc8
	v_readlane_b32 s4, v254, 32
	s_mov_b32 s6, s4
	s_mul_i32 s4, s4, 0x1600000
	v_readlane_b32 s5, v254, 33
	s_waitcnt lgkmcnt(0)
	s_add_u32 s0, s0, s4
	s_mul_hi_i32 s4, s6, 0x1600000
	s_addc_u32 s1, s1, s4
	s_mul_hi_i32 s4, s8, 0x2e8ba2e9
	s_lshr_b32 s5, s4, 31
	s_ashr_i32 s4, s4, 5
	s_add_i32 s5, s4, s5
	s_mul_i32 s6, s5, 0xffffea00
	s_add_i32 s6, s6, s9
	v_add_u32_e32 v2, s6, v18
	s_lshl_b32 s4, s5, 6
	v_ashrrev_i32_e32 v3, 31, v2
	v_lshl_add_u64 v[6:7], v[2:3], 2, s[0:1]
	v_add_u32_e32 v2, s4, v19
	s_movk_i32 s7, 0x5800
	v_mad_i64_i32 v[2:3], s[0:1], v2, s7, v[6:7]
	global_load_dwordx4 v[200:203], v[2:3], off nt
	v_add_u32_e32 v44, s6, v19
	s_mulk_i32 s5, 0xd400
	v_cmp_lt_i32_e32 vcc, s51, v44
	v_add_u32_e32 v43, s5, v0
	v_add_u32_e32 v2, s4, v20
	v_mad_i64_i32 v[2:3], s[0:1], v2, s7, v[6:7]
	global_load_dwordx4 v[204:207], v[2:3], off nt
	v_add_u32_e32 v2, s4, v21
	v_mad_i64_i32 v[2:3], s[0:1], v2, s7, v[6:7]
	global_load_dwordx4 v[208:211], v[2:3], off nt
	v_add_u32_e32 v2, s4, v22
	v_mad_i64_i32 v[2:3], s[0:1], v2, s7, v[6:7]
	global_load_dwordx4 v[212:215], v[2:3], off nt
	v_add_u32_e32 v2, s4, v23
	v_mad_i64_i32 v[2:3], s[0:1], v2, s7, v[6:7]
	global_load_dwordx4 v[216:219], v[2:3], off nt
	v_add_u32_e32 v2, s4, v24
	v_mad_i64_i32 v[2:3], s[0:1], v2, s7, v[6:7]
	global_load_dwordx4 v[220:223], v[2:3], off nt
	v_add_u32_e32 v2, s4, v25
	v_mad_i64_i32 v[2:3], s[0:1], v2, s7, v[6:7]
	global_load_dwordx4 v[224:227], v[2:3], off nt
	v_add_u32_e32 v2, s4, v26
	v_mad_i64_i32 v[2:3], s[0:1], v2, s7, v[6:7]
	global_load_dwordx4 v[228:231], v[2:3], off nt
	s_waitcnt vmcnt(7)
	ds_write2_b32 v28, v200, v201 offset1:1
	ds_write2_b32 v28, v202, v203 offset0:2 offset1:3
	s_waitcnt vmcnt(6)
	ds_write2_b32 v41, v204, v205 offset1:1
	ds_write2_b32 v42, v206, v207 offset1:1
	s_waitcnt vmcnt(5)
	ds_write2_b32 v37, v208, v209 offset1:1
	ds_write2_b32 v38, v210, v211 offset1:1
	s_waitcnt vmcnt(4)
	ds_write2_b32 v39, v212, v213 offset1:1
	ds_write2_b32 v40, v214, v215 offset1:1
	s_waitcnt vmcnt(3)
	ds_write2_b32 v33, v216, v217 offset1:1
	ds_write2_b32 v34, v218, v219 offset1:1
	s_waitcnt vmcnt(2)
	ds_write2_b32 v35, v220, v221 offset1:1
	ds_write2_b32 v36, v222, v223 offset1:1
	s_waitcnt vmcnt(1)
	ds_write2_b32 v29, v224, v225 offset1:1
	ds_write2_b32 v30, v226, v227 offset1:1
	s_waitcnt vmcnt(0)
	ds_write2_b32 v31, v228, v229 offset1:1
	ds_write2_b32 v32, v230, v231 offset1:1
	s_waitcnt lgkmcnt(0)
	ds_read2_b32 v[4:5], v27 offset1:33
	ds_read2_b32 v[6:7], v27 offset0:66 offset1:99
	ds_read2_b32 v[8:9], v27 offset0:132 offset1:165
	ds_read2_b32 v[14:15], v27 offset0:198 offset1:231
	v_and_b32_e32 v2, 0x7f, v44
	s_and_saveexec_b64 s[0:1], vcc
	s_xor_b64 s[6:7], exec, s[0:1]
	v_subrev_u32_e32 v3, 48, v43
	v_and_b32_e32 v3, 0x7fffff00, v3
	v_or3_b32 v16, v2, v3, s54
	s_andn2_saveexec_b64 s[6:7], s[6:7]
	v_add_u32_e32 v3, 0x800015d0, v43
	v_and_or_b32 v16, v3, s55, v2
	s_or_b64 exec, exec, s[6:7]
	s_ashr_i32 s5, s4, 31
	v_ashrrev_i32_e32 v17, 31, v16
	v_lshl_add_u64 v[2:3], s[4:5], 1, v[10:11]
	s_waitcnt lgkmcnt(3)
	v_cvt_pk_bf16_f32 v4, v4, v5
	s_waitcnt lgkmcnt(2)
	v_cvt_pk_bf16_f32 v5, v6, v7
	s_waitcnt lgkmcnt(1)
	v_cvt_pk_bf16_f32 v6, v8, v9
	v_lshlrev_b64 v[8:9], 11, v[16:17]
	s_waitcnt lgkmcnt(0)
	v_cvt_pk_bf16_f32 v7, v14, v15
	v_lshl_add_u64 v[8:9], v[2:3], 0, v[8:9]
	global_store_dwordx4 v[8:9], v[4:7], off
	ds_read2_b32 v[4:5], v27 offset0:8 offset1:41
	ds_read2_b32 v[6:7], v27 offset0:74 offset1:107
	ds_read2_b32 v[8:9], v27 offset0:140 offset1:173
	ds_read2_b32 v[14:15], v27 offset0:206 offset1:239
	v_add_u32_e32 v16, 8, v44
	v_cmp_lt_i32_e32 vcc, s51, v16
	v_and_b32_e32 v17, 0x7f, v16
	s_and_saveexec_b64 s[0:1], vcc
	s_xor_b64 s[4:5], exec, s[0:1]
	v_subrev_u32_e32 v16, 32, v43
	v_and_b32_e32 v16, 0x7fffff00, v16
	v_or3_b32 v16, v17, v16, s54
	s_andn2_saveexec_b64 s[4:5], s[4:5]
	v_add_u32_e32 v16, 0x800015e0, v43
	v_and_or_b32 v16, v16, s55, v17
	s_or_b64 exec, exec, s[4:5]
	v_ashrrev_i32_e32 v17, 31, v16
	s_waitcnt lgkmcnt(3)
	v_cvt_pk_bf16_f32 v4, v4, v5
	s_waitcnt lgkmcnt(2)
	v_cvt_pk_bf16_f32 v5, v6, v7
	s_waitcnt lgkmcnt(1)
	v_cvt_pk_bf16_f32 v6, v8, v9
	v_lshlrev_b64 v[8:9], 11, v[16:17]
	s_waitcnt lgkmcnt(0)
	v_cvt_pk_bf16_f32 v7, v14, v15
	v_lshl_add_u64 v[8:9], v[2:3], 0, v[8:9]
	global_store_dwordx4 v[8:9], v[4:7], off
	ds_read2_b32 v[4:5], v27 offset0:16 offset1:49
	ds_read2_b32 v[6:7], v27 offset0:82 offset1:115
	ds_read2_b32 v[8:9], v27 offset0:148 offset1:181
	ds_read2_b32 v[14:15], v27 offset0:214 offset1:247
	v_add_u32_e32 v16, 16, v44
	v_cmp_lt_i32_e32 vcc, s51, v16
	v_and_b32_e32 v17, 0x7f, v16
	s_and_saveexec_b64 s[0:1], vcc
	s_xor_b64 s[4:5], exec, s[0:1]
	v_add_u32_e32 v16, -16, v43
	v_and_b32_e32 v16, 0x7fffff00, v16
	v_or3_b32 v16, v17, v16, s54
	s_andn2_saveexec_b64 s[4:5], s[4:5]
	v_add_u32_e32 v16, 0x800015f0, v43
	v_and_or_b32 v16, v16, s55, v17
	s_or_b64 exec, exec, s[4:5]
	v_ashrrev_i32_e32 v17, 31, v16
	s_waitcnt lgkmcnt(3)
	v_cvt_pk_bf16_f32 v4, v4, v5
	s_waitcnt lgkmcnt(2)
	v_cvt_pk_bf16_f32 v5, v6, v7
	s_waitcnt lgkmcnt(1)
	v_cvt_pk_bf16_f32 v6, v8, v9
	v_lshlrev_b64 v[8:9], 11, v[16:17]
	s_waitcnt lgkmcnt(0)
	v_cvt_pk_bf16_f32 v7, v14, v15
	v_lshl_add_u64 v[8:9], v[2:3], 0, v[8:9]
	global_store_dwordx4 v[8:9], v[4:7], off
	ds_read2_b32 v[4:5], v27 offset0:24 offset1:57
	ds_read2_b32 v[6:7], v27 offset0:90 offset1:123
	ds_read2_b32 v[8:9], v27 offset0:156 offset1:189
	ds_read2_b32 v[14:15], v27 offset0:222 offset1:255
	v_add_u32_e32 v16, 24, v44
	v_cmp_lt_i32_e32 vcc, s51, v16
	v_and_b32_e32 v17, 0x7f, v16
	s_and_saveexec_b64 s[0:1], vcc
	s_xor_b64 s[4:5], exec, s[0:1]
	v_and_b32_e32 v16, 0x7fffff00, v43
	v_or3_b32 v16, v17, v16, s54
	s_andn2_saveexec_b64 s[4:5], s[4:5]
	v_add_u32_e32 v16, 0x80001600, v43
	v_and_or_b32 v16, v16, s55, v17
	s_or_b64 exec, exec, s[4:5]
	v_ashrrev_i32_e32 v17, 31, v16
	s_waitcnt lgkmcnt(3)
	v_cvt_pk_bf16_f32 v4, v4, v5
	s_waitcnt lgkmcnt(2)
	v_cvt_pk_bf16_f32 v5, v6, v7
	s_waitcnt lgkmcnt(1)
	v_cvt_pk_bf16_f32 v6, v8, v9
	v_lshlrev_b64 v[8:9], 11, v[16:17]
	s_waitcnt lgkmcnt(0)
	v_cvt_pk_bf16_f32 v7, v14, v15
	v_lshl_add_u64 v[2:3], v[2:3], 0, v[8:9]
	global_store_dwordx4 v[2:3], v[4:7], off
	s_waitcnt lgkmcnt(0)
	s_mov_b32 s12, s8

; #define LAS __attribute__((address_space(3)))
; template <int MAP>
; __device__ __forceinline__ void transpose_item(const float* W, int K, int N, bf16_t* WT, int ldk, LAS float* scr, int item, int nblk, int lane) {
;     ...
; #pragma unroll
;     for (int i = 0; i < 8; ++i) { const int kk = 8 * i + (lane >> 3); f32x4 v = {0.f, 0.f, 0.f, 0.f}; if (cc < N) v = *(const f32x4*)(W + (size_t)(k0 + kk) * N + cc);
;         LAS float* d = scr + kk * 33 + 4 * (lane & 7); d[0] = v.x; d[1] = v.y; d[2] = v.z; d[3] = v.w; }
.LBB0_149:
	s_or_saveexec_b64 s[4:5], s[2:3]
	s_lshl_b32 s0, s13, 1
	v_ashrrev_i32_e32 v3, 31, v2
	s_and_b32 s2, s0, 0xffffffc0
	v_lshl_add_u64 v[14:15], v[2:3], 2, s[6:7]
	v_mov_b32_e32 v6, 0
	v_mov_b32_e32 v7, 0
	v_mov_b32_e32 v8, 0
	v_mov_b32_e32 v9, 0
	v_mov_b32_e32 v2, 0
	v_mov_b32_e32 v3, 0
	v_mov_b32_e32 v4, 0
	v_mov_b32_e32 v5, 0
	s_xor_b64 exec, exec, s[4:5]
	s_cbranch_execz .LBB0_151
	v_add_u32_e32 v2, s2, v19
	v_ashrrev_i32_e32 v3, 31, v2
	v_lshlrev_b64 v[2:3], 12, v[2:3]
	v_add_u32_e32 v6, s2, v20
	v_lshl_add_u64 v[2:3], v[14:15], 0, v[2:3]
	v_ashrrev_i32_e32 v7, 31, v6
	global_load_dwordx4 v[2:5], v[2:3], off nt
	v_lshlrev_b64 v[6:7], 12, v[6:7]
	v_lshl_add_u64 v[6:7], v[14:15], 0, v[6:7]
	global_load_dwordx4 v[6:9], v[6:7], off nt
	s_waitcnt vmcnt(1)
	ds_write2_b32 v28, v2, v3 offset1:1
	ds_write2_b32 v28, v4, v5 offset0:2 offset1:3
	s_waitcnt vmcnt(0)
	ds_write2_b32 v41, v6, v7 offset1:1
	ds_write2_b32 v42, v8, v9 offset1:1
	v_add_u32_e32 v2, s2, v21
	v_add_u32_e32 v6, s2, v22
	v_ashrrev_i32_e32 v3, 31, v2
	v_ashrrev_i32_e32 v7, 31, v6
	v_lshlrev_b64 v[2:3], 12, v[2:3]
	v_lshlrev_b64 v[6:7], 12, v[6:7]
	v_lshl_add_u64 v[2:3], v[14:15], 0, v[2:3]
	v_lshl_add_u64 v[6:7], v[14:15], 0, v[6:7]
	global_load_dwordx4 v[2:5], v[2:3], off
	s_nop 0
	global_load_dwordx4 v[6:9], v[6:7], off

; #define LAS __attribute__((address_space(3)))
; template <int MAP>
; __device__ __forceinline__ void transpose_item(const float* W, int K, int N, bf16_t* WT, int ldk, LAS float* scr, int item, int nblk, int lane) {
;     ...
; #pragma unroll
;     for (int i = 0; i < 8; ++i) { const int kk = 8 * i + (lane >> 3); f32x4 v = {0.f, 0.f, 0.f, 0.f}; if (cc < N) v = *(const f32x4*)(W + (size_t)(k0 + kk) * N + cc);
;         LAS float* d = scr + kk * 33 + 4 * (lane & 7); d[0] = v.x; d[1] = v.y; d[2] = v.z; d[3] = v.w; }
.LBB0_467:
	s_or_saveexec_b64 s[6:7], s[6:7]
	v_mov_b32_e32 v6, 0
	v_mov_b32_e32 v7, 0
	v_mov_b32_e32 v8, 0
	v_mov_b32_e32 v9, 0
	v_mov_b32_e32 v2, 0
	v_mov_b32_e32 v3, 0
	v_mov_b32_e32 v4, 0
	v_mov_b32_e32 v5, 0
	s_xor_b64 exec, exec, s[6:7]
	s_cbranch_execz .LBB0_469
	v_add_u32_e32 v2, s4, v38
	v_ashrrev_i32_e32 v3, 31, v2
	v_add_u32_e32 v6, s4, v40
	v_lshlrev_b64 v[2:3], 12, v[2:3]
	v_ashrrev_i32_e32 v7, 31, v6
	v_lshl_add_u64 v[2:3], v[28:29], 0, v[2:3]
	v_lshlrev_b64 v[6:7], 12, v[6:7]
	global_load_dwordx4 v[2:5], v[2:3], off
	v_lshl_add_u64 v[6:7], v[28:29], 0, v[6:7]
	global_load_dwordx4 v[6:9], v[6:7], off
	v_add_u32_e32 v0, v32, v39
	s_waitcnt vmcnt(1)
	ds_write2_b32 v0, v2, v3 offset1:1
	ds_write2_b32 v0, v4, v5 offset0:2 offset1:3
	v_add_u32_e32 v2, 0x420, v0
	s_waitcnt vmcnt(0)
	ds_write2_b32 v2, v6, v7 offset1:1
	v_add_u32_e32 v2, s4, v41
	v_add_u32_e32 v6, s4, v42
	v_ashrrev_i32_e32 v3, 31, v2
	v_ashrrev_i32_e32 v7, 31, v6
	v_lshlrev_b64 v[2:3], 12, v[2:3]
	v_lshlrev_b64 v[6:7], 12, v[6:7]
	v_add_u32_e32 v0, 0x428, v0
	v_lshl_add_u64 v[2:3], v[28:29], 0, v[2:3]
	v_lshl_add_u64 v[6:7], v[28:29], 0, v[6:7]
	ds_write2_b32 v0, v8, v9 offset1:1
	global_load_dwordx4 v[2:5], v[2:3], off nt
	s_nop 0
	global_load_dwordx4 v[6:9], v[6:7], off nt

; #define LAS __attribute__((address_space(3)))
; template <int MAP>
; __device__ __forceinline__ void transpose_item(const float* W, int K, int N, bf16_t* WT, int ldk, LAS float* scr, int item, int nblk, int lane) {
;     ...
; #pragma unroll
;     for (int i = 0; i < 8; ++i) { const int kk = 8 * i + (lane >> 3); f32x4 v = {0.f, 0.f, 0.f, 0.f}; if (cc < N) v = *(const f32x4*)(W + (size_t)(k0 + kk) * N + cc);
;         LAS float* d = scr + kk * 33 + 4 * (lane & 7); d[0] = v.x; d[1] = v.y; d[2] = v.z; d[3] = v.w; }
.LBB0_476:
	s_or_saveexec_b64 s[6:7], s[4:5]
	v_readlane_b32 s0, v254, 36
	v_readlane_b32 s1, v254, 37
	s_load_dwordx2 s[0:1], s[0:1], 0x80
	s_lshl_b32 s4, s13, 4
	v_ashrrev_i32_e32 v3, 31, v2
	v_mov_b32_e32 v6, 0
	s_andn2_b32 s4, s4, 63
	s_waitcnt lgkmcnt(0)
	v_lshl_add_u64 v[28:29], v[2:3], 2, s[0:1]
	v_mov_b32_e32 v7, 0
	v_mov_b32_e32 v8, 0
	v_mov_b32_e32 v9, 0
	v_mov_b32_e32 v2, 0
	v_mov_b32_e32 v3, 0
	v_mov_b32_e32 v4, 0
	v_mov_b32_e32 v5, 0
	s_xor_b64 exec, exec, s[6:7]
	s_cbranch_execz .LBB0_478
	v_add_u32_e32 v2, s4, v31
	v_ashrrev_i32_e32 v3, 31, v2
	v_add_u32_e32 v6, s4, v34
	v_lshlrev_b64 v[2:3], 9, v[2:3]
	v_ashrrev_i32_e32 v7, 31, v6
	v_lshl_add_u64 v[2:3], v[28:29], 0, v[2:3]
	v_lshlrev_b64 v[6:7], 9, v[6:7]
	global_load_dwordx4 v[2:5], v[2:3], off nt
	v_lshl_add_u64 v[6:7], v[28:29], 0, v[6:7]
	global_load_dwordx4 v[6:9], v[6:7], off nt
	v_add_u32_e32 v0, v32, v33
	s_waitcnt vmcnt(0)
	ds_write2_b32 v0, v2, v3 offset1:1
	ds_write2_b32 v0, v4, v5 offset0:2 offset1:3
	v_add_u32_e32 v2, 0x420, v0
	ds_write2_b32 v2, v6, v7 offset1:1
	v_add_u32_e32 v2, s4, v35
	v_add_u32_e32 v6, s4, v37
	v_ashrrev_i32_e32 v3, 31, v2
	v_ashrrev_i32_e32 v7, 31, v6
	v_lshlrev_b64 v[2:3], 9, v[2:3]
	v_lshlrev_b64 v[6:7], 9, v[6:7]
	v_add_u32_e32 v0, 0x428, v0
	v_lshl_add_u64 v[2:3], v[28:29], 0, v[2:3]
	v_lshl_add_u64 v[6:7], v[28:29], 0, v[6:7]
	ds_write2_b32 v0, v8, v9 offset1:1
	global_load_dwordx4 v[2:5], v[2:3], off nt
	s_nop 0
	global_load_dwordx4 v[6:9], v[6:7], off nt

; #define LAS __attribute__((address_space(3)))
; template <int MAP>
; __device__ __forceinline__ void transpose_item(const float* W, int K, int N, bf16_t* WT, int ldk, LAS float* scr, int item, int nblk, int lane) {
;     ...
; #pragma unroll
;     for (int i = 0; i < 8; ++i) { const int kk = 8 * i + (lane >> 3); f32x4 v = {0.f, 0.f, 0.f, 0.f}; if (cc < N) v = *(const f32x4*)(W + (size_t)(k0 + kk) * N + cc);
;         LAS float* d = scr + kk * 33 + 4 * (lane & 7); d[0] = v.x; d[1] = v.y; d[2] = v.z; d[3] = v.w; }
.LBB0_480:
	s_or_saveexec_b64 s[6:7], s[6:7]
	v_mov_b32_e32 v6, 0
	v_mov_b32_e32 v7, 0
	v_mov_b32_e32 v8, 0
	v_mov_b32_e32 v9, 0
	v_mov_b32_e32 v2, 0
	v_mov_b32_e32 v3, 0
	v_mov_b32_e32 v4, 0
	v_mov_b32_e32 v5, 0
	s_xor_b64 exec, exec, s[6:7]
	s_cbranch_execz .LBB0_482
	v_add_u32_e32 v2, s4, v38
	v_ashrrev_i32_e32 v3, 31, v2
	v_add_u32_e32 v6, s4, v40
	v_lshlrev_b64 v[2:3], 9, v[2:3]
	v_ashrrev_i32_e32 v7, 31, v6
	v_lshl_add_u64 v[2:3], v[28:29], 0, v[2:3]
	v_lshlrev_b64 v[6:7], 9, v[6:7]
	global_load_dwordx4 v[2:5], v[2:3], off nt
	v_lshl_add_u64 v[6:7], v[28:29], 0, v[6:7]
	global_load_dwordx4 v[6:9], v[6:7], off nt
	v_add_u32_e32 v0, v32, v39
	s_waitcnt vmcnt(1)
	ds_write2_b32 v0, v2, v3 offset1:1
	ds_write2_b32 v0, v4, v5 offset0:2 offset1:3
	v_add_u32_e32 v2, 0x420, v0
	s_waitcnt vmcnt(0)
	ds_write2_b32 v2, v6, v7 offset1:1
	v_add_u32_e32 v2, s4, v41
	v_add_u32_e32 v6, s4, v42
	v_ashrrev_i32_e32 v3, 31, v2
	v_ashrrev_i32_e32 v7, 31, v6
	v_lshlrev_b64 v[2:3], 9, v[2:3]
	v_lshlrev_b64 v[6:7], 9, v[6:7]
	v_add_u32_e32 v0, 0x428, v0
	v_lshl_add_u64 v[2:3], v[28:29], 0, v[2:3]
	v_lshl_add_u64 v[6:7], v[28:29], 0, v[6:7]
	ds_write2_b32 v0, v8, v9 offset1:1
	global_load_dwordx4 v[2:5], v[2:3], off nt
	s_nop 0
	global_load_dwordx4 v[6:9], v[6:7], off nt

; #define LAS __attribute__((address_space(3)))
; template <int MAP>
; __device__ __forceinline__ void transpose_item(const float* W, int K, int N, bf16_t* WT, int ldk, LAS float* scr, int item, int nblk, int lane) {
;     ...
; #pragma unroll
;     for (int i = 0; i < 8; ++i) { const int kk = 8 * i + (lane >> 3); f32x4 v = {0.f, 0.f, 0.f, 0.f}; if (cc < N) v = *(const f32x4*)(W + (size_t)(k0 + kk) * N + cc);
;         LAS float* d = scr + kk * 33 + 4 * (lane & 7); d[0] = v.x; d[1] = v.y; d[2] = v.z; d[3] = v.w; }
.LBB0_489:
	s_or_saveexec_b64 s[6:7], s[4:5]
	v_readlane_b32 s0, v254, 36
	v_readlane_b32 s1, v254, 37
	s_load_dwordx2 s[0:1], s[0:1], 0x90
	s_lshl_b32 s4, s13, 4
	v_ashrrev_i32_e32 v3, 31, v2
	v_mov_b32_e32 v6, 0
	s_andn2_b32 s4, s4, 63
	s_waitcnt lgkmcnt(0)
	v_lshl_add_u64 v[28:29], v[2:3], 2, s[0:1]
	v_mov_b32_e32 v7, 0
	v_mov_b32_e32 v8, 0
	v_mov_b32_e32 v9, 0
	v_mov_b32_e32 v2, 0
	v_mov_b32_e32 v3, 0
	v_mov_b32_e32 v4, 0
	v_mov_b32_e32 v5, 0
	s_xor_b64 exec, exec, s[6:7]
	s_cbranch_execz .LBB0_491
	v_add_u32_e32 v2, s4, v31
	v_ashrrev_i32_e32 v3, 31, v2
	v_add_u32_e32 v6, s4, v34
	v_lshlrev_b64 v[2:3], 9, v[2:3]
	v_ashrrev_i32_e32 v7, 31, v6
	v_lshl_add_u64 v[2:3], v[28:29], 0, v[2:3]
	v_lshlrev_b64 v[6:7], 9, v[6:7]
	global_load_dwordx4 v[2:5], v[2:3], off nt
	v_lshl_add_u64 v[6:7], v[28:29], 0, v[6:7]
	global_load_dwordx4 v[6:9], v[6:7], off nt
	v_add_u32_e32 v0, v32, v33
	s_waitcnt vmcnt(0)
	ds_write2_b32 v0, v2, v3 offset1:1
	ds_write2_b32 v0, v4, v5 offset0:2 offset1:3
	v_add_u32_e32 v2, 0x420, v0
	ds_write2_b32 v2, v6, v7 offset1:1
	v_add_u32_e32 v2, s4, v35
	v_add_u32_e32 v6, s4, v37
	v_ashrrev_i32_e32 v3, 31, v2
	v_ashrrev_i32_e32 v7, 31, v6
	v_lshlrev_b64 v[2:3], 9, v[2:3]
	v_lshlrev_b64 v[6:7], 9, v[6:7]
	v_add_u32_e32 v0, 0x428, v0
	v_lshl_add_u64 v[2:3], v[28:29], 0, v[2:3]
	v_lshl_add_u64 v[6:7], v[28:29], 0, v[6:7]
	ds_write2_b32 v0, v8, v9 offset1:1
	global_load_dwordx4 v[2:5], v[2:3], off nt
	s_nop 0
	global_load_dwordx4 v[6:9], v[6:7], off nt

; #define LAS __attribute__((address_space(3)))
; template <int MAP>
; __device__ __forceinline__ void transpose_item(const float* W, int K, int N, bf16_t* WT, int ldk, LAS float* scr, int item, int nblk, int lane) {
;     ...
; #pragma unroll
;     for (int i = 0; i < 8; ++i) { const int kk = 8 * i + (lane >> 3); f32x4 v = {0.f, 0.f, 0.f, 0.f}; if (cc < N) v = *(const f32x4*)(W + (size_t)(k0 + kk) * N + cc);
;         LAS float* d = scr + kk * 33 + 4 * (lane & 7); d[0] = v.x; d[1] = v.y; d[2] = v.z; d[3] = v.w; }
.LBB0_502:
	s_or_saveexec_b64 s[6:7], s[4:5]
	v_readlane_b32 s0, v254, 36
	v_readlane_b32 s1, v254, 37
	s_load_dwordx2 s[0:1], s[0:1], 0xa0
	s_lshl_b32 s4, s13, 1
	v_ashrrev_i32_e32 v3, 31, v2
	v_mov_b32_e32 v6, 0
	s_andn2_b32 s4, s4, 63
	s_waitcnt lgkmcnt(0)
	v_lshl_add_u64 v[28:29], v[2:3], 2, s[0:1]
	v_mov_b32_e32 v7, 0
	v_mov_b32_e32 v8, 0
	v_mov_b32_e32 v9, 0
	v_mov_b32_e32 v2, 0
	v_mov_b32_e32 v3, 0
	v_mov_b32_e32 v4, 0
	v_mov_b32_e32 v5, 0
	s_xor_b64 exec, exec, s[6:7]
	s_cbranch_execz .LBB0_504
	v_add_u32_e32 v2, s4, v31
	v_ashrrev_i32_e32 v3, 31, v2
	v_add_u32_e32 v6, s4, v34
	v_lshlrev_b64 v[2:3], 12, v[2:3]
	v_ashrrev_i32_e32 v7, 31, v6
	v_lshl_add_u64 v[2:3], v[28:29], 0, v[2:3]
	v_lshlrev_b64 v[6:7], 12, v[6:7]
	global_load_dwordx4 v[2:5], v[2:3], off nt
	v_lshl_add_u64 v[6:7], v[28:29], 0, v[6:7]
	global_load_dwordx4 v[6:9], v[6:7], off nt
	v_add_u32_e32 v0, v32, v33
	s_waitcnt vmcnt(0)
	ds_write2_b32 v0, v2, v3 offset1:1
	ds_write2_b32 v0, v4, v5 offset0:2 offset1:3
	v_add_u32_e32 v2, 0x420, v0
	ds_write2_b32 v2, v6, v7 offset1:1
	v_add_u32_e32 v2, s4, v35
	v_add_u32_e32 v6, s4, v37
	v_ashrrev_i32_e32 v3, 31, v2
	v_ashrrev_i32_e32 v7, 31, v6
	v_lshlrev_b64 v[2:3], 12, v[2:3]
	v_lshlrev_b64 v[6:7], 12, v[6:7]
	v_add_u32_e32 v0, 0x428, v0
	v_lshl_add_u64 v[2:3], v[28:29], 0, v[2:3]
	v_lshl_add_u64 v[6:7], v[28:29], 0, v[6:7]
	ds_write2_b32 v0, v8, v9 offset1:1
	global_load_dwordx4 v[2:5], v[2:3], off nt
	s_nop 0
	global_load_dwordx4 v[6:9], v[6:7], off nt

; #define LAS __attribute__((address_space(3)))
; template <int MAP>
; __device__ __forceinline__ void transpose_item(const float* W, int K, int N, bf16_t* WT, int ldk, LAS float* scr, int item, int nblk, int lane) {
;     ...
; #pragma unroll
;     for (int i = 0; i < 8; ++i) { const int kk = 8 * i + (lane >> 3); f32x4 v = {0.f, 0.f, 0.f, 0.f}; if (cc < N) v = *(const f32x4*)(W + (size_t)(k0 + kk) * N + cc);
;         LAS float* d = scr + kk * 33 + 4 * (lane & 7); d[0] = v.x; d[1] = v.y; d[2] = v.z; d[3] = v.w; }
.LBB0_506:
	s_or_saveexec_b64 s[6:7], s[6:7]
	v_mov_b32_e32 v6, 0
	v_mov_b32_e32 v7, 0
	v_mov_b32_e32 v8, 0
	v_mov_b32_e32 v9, 0
	v_mov_b32_e32 v2, 0
	v_mov_b32_e32 v3, 0
	v_mov_b32_e32 v4, 0
	v_mov_b32_e32 v5, 0
	s_xor_b64 exec, exec, s[6:7]
	s_cbranch_execz .LBB0_508
	v_add_u32_e32 v2, s4, v38
	v_ashrrev_i32_e32 v3, 31, v2
	v_add_u32_e32 v6, s4, v40
	v_lshlrev_b64 v[2:3], 12, v[2:3]
	v_ashrrev_i32_e32 v7, 31, v6
	v_lshl_add_u64 v[2:3], v[28:29], 0, v[2:3]
	v_lshlrev_b64 v[6:7], 12, v[6:7]
	global_load_dwordx4 v[2:5], v[2:3], off nt
	v_lshl_add_u64 v[6:7], v[28:29], 0, v[6:7]
	global_load_dwordx4 v[6:9], v[6:7], off nt
	v_add_u32_e32 v0, v32, v39
	s_waitcnt vmcnt(1)
	ds_write2_b32 v0, v2, v3 offset1:1
	ds_write2_b32 v0, v4, v5 offset0:2 offset1:3
	v_add_u32_e32 v2, 0x420, v0
	s_waitcnt vmcnt(0)
	ds_write2_b32 v2, v6, v7 offset1:1
	v_add_u32_e32 v2, s4, v41
	v_add_u32_e32 v6, s4, v42
	v_ashrrev_i32_e32 v3, 31, v2
	v_ashrrev_i32_e32 v7, 31, v6
	v_lshlrev_b64 v[2:3], 12, v[2:3]
	v_lshlrev_b64 v[6:7], 12, v[6:7]
	v_add_u32_e32 v0, 0x428, v0
	v_lshl_add_u64 v[2:3], v[28:29], 0, v[2:3]
	v_lshl_add_u64 v[6:7], v[28:29], 0, v[6:7]
	ds_write2_b32 v0, v8, v9 offset1:1
	global_load_dwordx4 v[2:5], v[2:3], off nt
	s_nop 0
	global_load_dwordx4 v[6:9], v[6:7], off nt

; #define LAS __attribute__((address_space(3)))
; template <int MAP>
; __device__ __forceinline__ void transpose_item(const float* W, int K, int N, bf16_t* WT, int ldk, LAS float* scr, int item, int nblk, int lane) {
;     ...
; #pragma unroll
;     for (int i = 0; i < 8; ++i) { const int kk = 8 * i + (lane >> 3); f32x4 v = {0.f, 0.f, 0.f, 0.f}; if (cc < N) v = *(const f32x4*)(W + (size_t)(k0 + kk) * N + cc);
;         LAS float* d = scr + kk * 33 + 4 * (lane & 7); d[0] = v.x; d[1] = v.y; d[2] = v.z; d[3] = v.w; }
.LBB0_515:
	s_or_saveexec_b64 s[6:7], s[4:5]
	v_readlane_b32 s0, v254, 36
	v_readlane_b32 s1, v254, 37
	s_load_dwordx2 s[0:1], s[0:1], 0xa8
	s_lshl_b32 s4, s13, 1
	v_ashrrev_i32_e32 v3, 31, v2
	v_mov_b32_e32 v6, 0
	s_andn2_b32 s4, s4, 63
	s_waitcnt lgkmcnt(0)
	v_lshl_add_u64 v[28:29], v[2:3], 2, s[0:1]
	v_mov_b32_e32 v7, 0
	v_mov_b32_e32 v8, 0
	v_mov_b32_e32 v9, 0
	v_mov_b32_e32 v2, 0
	v_mov_b32_e32 v3, 0
	v_mov_b32_e32 v4, 0
	v_mov_b32_e32 v5, 0
	s_xor_b64 exec, exec, s[6:7]
	s_cbranch_execz .LBB0_517
	v_add_u32_e32 v2, s4, v31
	v_ashrrev_i32_e32 v3, 31, v2
	v_add_u32_e32 v6, s4, v34
	v_lshlrev_b64 v[2:3], 12, v[2:3]
	v_ashrrev_i32_e32 v7, 31, v6
	v_lshl_add_u64 v[2:3], v[28:29], 0, v[2:3]
	v_lshlrev_b64 v[6:7], 12, v[6:7]
	global_load_dwordx4 v[2:5], v[2:3], off nt
	v_lshl_add_u64 v[6:7], v[28:29], 0, v[6:7]
	global_load_dwordx4 v[6:9], v[6:7], off nt
	v_add_u32_e32 v0, v32, v33
	s_waitcnt vmcnt(0)
	ds_write2_b32 v0, v2, v3 offset1:1
	ds_write2_b32 v0, v4, v5 offset0:2 offset1:3
	v_add_u32_e32 v2, 0x420, v0
	ds_write2_b32 v2, v6, v7 offset1:1
	v_add_u32_e32 v2, s4, v35
	v_add_u32_e32 v6, s4, v37
	v_ashrrev_i32_e32 v3, 31, v2
	v_ashrrev_i32_e32 v7, 31, v6
	v_lshlrev_b64 v[2:3], 12, v[2:3]
	v_lshlrev_b64 v[6:7], 12, v[6:7]
	v_add_u32_e32 v0, 0x428, v0
	v_lshl_add_u64 v[2:3], v[28:29], 0, v[2:3]
	v_lshl_add_u64 v[6:7], v[28:29], 0, v[6:7]
	ds_write2_b32 v0, v8, v9 offset1:1
	global_load_dwordx4 v[2:5], v[2:3], off nt
	s_nop 0
	global_load_dwordx4 v[6:9], v[6:7], off nt

; #define LAS __attribute__((address_space(3)))
; template <int MAP>
; __device__ __forceinline__ void transpose_item(const float* W, int K, int N, bf16_t* WT, int ldk, LAS float* scr, int item, int nblk, int lane) {
;     ...
; #pragma unroll
;     for (int i = 0; i < 8; ++i) { const int kk = 8 * i + (lane >> 3); f32x4 v = {0.f, 0.f, 0.f, 0.f}; if (cc < N) v = *(const f32x4*)(W + (size_t)(k0 + kk) * N + cc);
;         LAS float* d = scr + kk * 33 + 4 * (lane & 7); d[0] = v.x; d[1] = v.y; d[2] = v.z; d[3] = v.w; }
.LBB0_527:
	s_or_saveexec_b64 s[6:7], s[4:5]
	v_readlane_b32 s0, v254, 36
	v_readlane_b32 s1, v254, 37
	s_load_dwordx2 s[0:1], s[0:1], 0xb0
	s_lshl_b32 s4, s13, 1
	v_ashrrev_i32_e32 v3, 31, v2
	v_mov_b32_e32 v6, 0
	s_andn2_b32 s4, s4, 63
	s_waitcnt lgkmcnt(0)
	v_lshl_add_u64 v[28:29], v[2:3], 2, s[0:1]
	v_mov_b32_e32 v7, 0
	v_mov_b32_e32 v8, 0
	v_mov_b32_e32 v9, 0
	v_mov_b32_e32 v2, 0
	v_mov_b32_e32 v3, 0
	v_mov_b32_e32 v4, 0
	v_mov_b32_e32 v5, 0
	s_xor_b64 exec, exec, s[6:7]
	s_cbranch_execz .LBB0_529
	v_add_u32_e32 v2, s4, v31
	v_ashrrev_i32_e32 v3, 31, v2
	v_add_u32_e32 v6, s4, v34
	v_lshlrev_b64 v[2:3], 12, v[2:3]
	v_ashrrev_i32_e32 v7, 31, v6
	v_lshl_add_u64 v[2:3], v[28:29], 0, v[2:3]
	v_lshlrev_b64 v[6:7], 12, v[6:7]
	global_load_dwordx4 v[2:5], v[2:3], off nt
	v_lshl_add_u64 v[6:7], v[28:29], 0, v[6:7]
	global_load_dwordx4 v[6:9], v[6:7], off nt
	v_add_u32_e32 v0, v32, v33
	s_waitcnt vmcnt(0)
	ds_write2_b32 v0, v2, v3 offset1:1
	ds_write2_b32 v0, v4, v5 offset0:2 offset1:3
	v_add_u32_e32 v2, 0x420, v0
	ds_write2_b32 v2, v6, v7 offset1:1
	v_add_u32_e32 v2, s4, v35
	v_add_u32_e32 v6, s4, v37
	v_ashrrev_i32_e32 v3, 31, v2
	v_ashrrev_i32_e32 v7, 31, v6
	v_lshlrev_b64 v[2:3], 12, v[2:3]
	v_lshlrev_b64 v[6:7], 12, v[6:7]
	v_add_u32_e32 v0, 0x428, v0
	v_lshl_add_u64 v[2:3], v[28:29], 0, v[2:3]
	v_lshl_add_u64 v[6:7], v[28:29], 0, v[6:7]
	ds_write2_b32 v0, v8, v9 offset1:1
	global_load_dwordx4 v[2:5], v[2:3], off nt
	s_nop 0
	global_load_dwordx4 v[6:9], v[6:7], off nt

; #define LAS __attribute__((address_space(3)))
; template <int MAP>
; __device__ __forceinline__ void transpose_item(const float* W, int K, int N, bf16_t* WT, int ldk, LAS float* scr, int item, int nblk, int lane) {
;     ...
; #pragma unroll
;     for (int i = 0; i < 8; ++i) { const int kk = 8 * i + (lane >> 3); f32x4 v = {0.f, 0.f, 0.f, 0.f}; if (cc < N) v = *(const f32x4*)(W + (size_t)(k0 + kk) * N + cc);
;         LAS float* d = scr + kk * 33 + 4 * (lane & 7); d[0] = v.x; d[1] = v.y; d[2] = v.z; d[3] = v.w; }
.LBB0_537:
	s_or_saveexec_b64 s[4:5], s[2:3]
	v_readlane_b32 s0, v254, 36
	v_readlane_b32 s1, v254, 37
	s_load_dwordx2 s[0:1], s[0:1], 0xb8
	s_lshl_b32 s2, s7, 1
	v_ashrrev_i32_e32 v3, 31, v2
	v_mov_b32_e32 v6, 0
	s_andn2_b32 s2, s2, 63
	s_waitcnt lgkmcnt(0)
	v_lshl_add_u64 v[28:29], v[2:3], 2, s[0:1]
	v_mov_b32_e32 v7, 0
	v_mov_b32_e32 v8, 0
	v_mov_b32_e32 v9, 0
	v_mov_b32_e32 v2, 0
	v_mov_b32_e32 v3, 0
	v_mov_b32_e32 v4, 0
	v_mov_b32_e32 v5, 0
	s_xor_b64 exec, exec, s[4:5]
	s_cbranch_execz .LBB0_539
	v_add_u32_e32 v2, s2, v31
	v_ashrrev_i32_e32 v3, 31, v2
	v_lshlrev_b64 v[2:3], 12, v[2:3]
	v_add_u32_e32 v6, s2, v34
	v_lshl_add_u64 v[2:3], v[28:29], 0, v[2:3]
	v_ashrrev_i32_e32 v7, 31, v6
	global_load_dwordx4 v[2:5], v[2:3], off nt
	v_lshlrev_b64 v[6:7], 12, v[6:7]
	v_lshl_add_u64 v[6:7], v[28:29], 0, v[6:7]
	global_load_dwordx4 v[6:9], v[6:7], off nt
	s_waitcnt vmcnt(0)
	ds_write2_b32 v0, v2, v3 offset1:1
	ds_write2_b32 v0, v4, v5 offset0:2 offset1:3
	ds_write2_b32 v44, v6, v7 offset1:1
	ds_write2_b32 v45, v8, v9 offset1:1
	v_add_u32_e32 v2, s2, v35
	v_add_u32_e32 v6, s2, v37
	v_ashrrev_i32_e32 v3, 31, v2
	v_ashrrev_i32_e32 v7, 31, v6
	v_lshlrev_b64 v[2:3], 12, v[2:3]
	v_lshlrev_b64 v[6:7], 12, v[6:7]
	v_lshl_add_u64 v[2:3], v[28:29], 0, v[2:3]
	v_lshl_add_u64 v[6:7], v[28:29], 0, v[6:7]
	global_load_dwordx4 v[2:5], v[2:3], off nt
	s_nop 0
	global_load_dwordx4 v[6:9], v[6:7], off nt

; #define LAS __attribute__((address_space(3)))
; template <int MAP>
; __device__ __forceinline__ void transpose_item(const float* W, int K, int N, bf16_t* WT, int ldk, LAS float* scr, int item, int nblk, int lane) {
;     ...
; #pragma unroll
;     for (int i = 0; i < 8; ++i) { const int kk = 8 * i + (lane >> 3); f32x4 v = {0.f, 0.f, 0.f, 0.f}; if (cc < N) v = *(const f32x4*)(W + (size_t)(k0 + kk) * N + cc);
;         LAS float* d = scr + kk * 33 + 4 * (lane & 7); d[0] = v.x; d[1] = v.y; d[2] = v.z; d[3] = v.w; }
.LBB0_541:
	s_or_saveexec_b64 s[4:5], s[4:5]
	v_mov_b32_e32 v6, 0
	v_mov_b32_e32 v7, 0
	v_mov_b32_e32 v8, 0
	v_mov_b32_e32 v9, 0
	v_mov_b32_e32 v2, 0
	v_mov_b32_e32 v3, 0
	v_mov_b32_e32 v4, 0
	v_mov_b32_e32 v5, 0
	s_xor_b64 exec, exec, s[4:5]
	s_cbranch_execz .LBB0_429
	v_add_u32_e32 v2, s2, v38
	v_ashrrev_i32_e32 v3, 31, v2
	v_lshlrev_b64 v[2:3], 12, v[2:3]
	v_add_u32_e32 v6, s2, v40
	v_lshl_add_u64 v[2:3], v[28:29], 0, v[2:3]
	v_ashrrev_i32_e32 v7, 31, v6
	global_load_dwordx4 v[2:5], v[2:3], off nt
	v_lshlrev_b64 v[6:7], 12, v[6:7]
	v_lshl_add_u64 v[6:7], v[28:29], 0, v[6:7]
	global_load_dwordx4 v[6:9], v[6:7], off nt
	s_waitcnt vmcnt(1)
	ds_write2_b32 v0, v2, v3 offset1:1
	ds_write2_b32 v0, v4, v5 offset0:2 offset1:3
	s_waitcnt vmcnt(0)
	ds_write2_b32 v44, v6, v7 offset1:1
	ds_write2_b32 v45, v8, v9 offset1:1
	v_add_u32_e32 v2, s2, v41
	v_add_u32_e32 v6, s2, v42
	v_ashrrev_i32_e32 v3, 31, v2
	v_ashrrev_i32_e32 v7, 31, v6
	v_lshlrev_b64 v[2:3], 12, v[2:3]
	v_lshlrev_b64 v[6:7], 12, v[6:7]
	v_lshl_add_u64 v[2:3], v[28:29], 0, v[2:3]
	v_lshl_add_u64 v[6:7], v[28:29], 0, v[6:7]
	global_load_dwordx4 v[2:5], v[2:3], off nt
	s_nop 0
	global_load_dwordx4 v[6:9], v[6:7], off nt
	s_branch .LBB0_429

; #define LAS __attribute__((address_space(3)))
; template <int MAP>
; __device__ __forceinline__ void transpose_item(const float* W, int K, int N, bf16_t* WT, int ldk, LAS float* scr, int item, int nblk, int lane) {
;     ...
; #pragma unroll
;     for (int i = 0; i < 8; ++i) { const int kk = 8 * i + (lane >> 3); f32x4 v = {0.f, 0.f, 0.f, 0.f}; if (cc < N) v = *(const f32x4*)(W + (size_t)(k0 + kk) * N + cc);
;         LAS float* d = scr + kk * 33 + 4 * (lane & 7); d[0] = v.x; d[1] = v.y; d[2] = v.z; d[3] = v.w; }
.LBB0_557:
	s_or_saveexec_b64 s[14:15], s[12:13]
	v_ashrrev_i32_e32 v3, 31, v2
	s_lshl_b32 s12, s24, 6
	v_lshl_add_u64 v[26:27], v[2:3], 2, s[16:17]
	v_mov_b32_e32 v6, 0
	v_mov_b32_e32 v7, 0
	v_mov_b32_e32 v8, 0
	v_mov_b32_e32 v9, 0
	v_mov_b32_e32 v2, 0
	v_mov_b32_e32 v3, 0
	v_mov_b32_e32 v4, 0
	v_mov_b32_e32 v5, 0
	s_xor_b64 exec, exec, s[14:15]
	s_cbranch_execz .LBB0_559
	v_add_u32_e32 v2, s12, v29
	s_movk_i32 s13, 0xc00
	v_mad_i64_i32 v[2:3], s[0:1], v2, s13, v[26:27]
	v_add_u32_e32 v6, s12, v32
	global_load_dwordx4 v[2:5], v[2:3], off nt
	v_mad_i64_i32 v[6:7], s[0:1], v6, s13, v[26:27]
	global_load_dwordx4 v[6:9], v[6:7], off nt
	v_add_u32_e32 v43, v30, v31
	s_waitcnt vmcnt(0)
	ds_write2_b32 v43, v2, v3 offset1:1
	ds_write2_b32 v43, v4, v5 offset0:2 offset1:3
	v_add_u32_e32 v2, 0x420, v43
	ds_write2_b32 v2, v6, v7 offset1:1
	v_add_u32_e32 v2, 0x428, v43
	ds_write2_b32 v2, v8, v9 offset1:1
	v_add_u32_e32 v2, s12, v33
	v_add_u32_e32 v6, s12, v35
	v_mad_i64_i32 v[2:3], s[0:1], v2, s13, v[26:27]
	v_mad_i64_i32 v[6:7], s[0:1], v6, s13, v[26:27]
	global_load_dwordx4 v[2:5], v[2:3], off nt
	s_nop 0
	global_load_dwordx4 v[6:9], v[6:7], off nt

; #define LAS __attribute__((address_space(3)))
; template <int MAP>
; __device__ __forceinline__ void transpose_item(const float* W, int K, int N, bf16_t* WT, int ldk, LAS float* scr, int item, int nblk, int lane) {
;     ...
; #pragma unroll
;     for (int i = 0; i < 8; ++i) { const int kk = 8 * i + (lane >> 3); f32x4 v = {0.f, 0.f, 0.f, 0.f}; if (cc < N) v = *(const f32x4*)(W + (size_t)(k0 + kk) * N + cc);
;         LAS float* d = scr + kk * 33 + 4 * (lane & 7); d[0] = v.x; d[1] = v.y; d[2] = v.z; d[3] = v.w; }
.LBB0_561:
	s_or_saveexec_b64 s[14:15], s[14:15]
	v_mov_b32_e32 v6, 0
	v_mov_b32_e32 v7, 0
	v_mov_b32_e32 v8, 0
	v_mov_b32_e32 v9, 0
	v_mov_b32_e32 v2, 0
	v_mov_b32_e32 v3, 0
	v_mov_b32_e32 v4, 0
	v_mov_b32_e32 v5, 0
	s_xor_b64 exec, exec, s[14:15]
	s_cbranch_execz .LBB0_563
	v_add_u32_e32 v2, s12, v36
	s_movk_i32 s13, 0xc00
	v_mad_i64_i32 v[2:3], s[0:1], v2, s13, v[26:27]
	v_add_u32_e32 v6, s12, v38
	global_load_dwordx4 v[2:5], v[2:3], off nt
	v_mad_i64_i32 v[6:7], s[0:1], v6, s13, v[26:27]
	global_load_dwordx4 v[6:9], v[6:7], off nt
	v_add_u32_e32 v43, v30, v37
	s_waitcnt vmcnt(1)
	ds_write2_b32 v43, v2, v3 offset1:1
	ds_write2_b32 v43, v4, v5 offset0:2 offset1:3
	v_add_u32_e32 v2, 0x420, v43
	s_waitcnt vmcnt(0)
	ds_write2_b32 v2, v6, v7 offset1:1
	v_add_u32_e32 v2, 0x428, v43
	ds_write2_b32 v2, v8, v9 offset1:1
	v_add_u32_e32 v2, s12, v39
	v_add_u32_e32 v6, s12, v40
	v_mad_i64_i32 v[2:3], s[0:1], v2, s13, v[26:27]
	v_mad_i64_i32 v[6:7], s[0:1], v6, s13, v[26:27]
	global_load_dwordx4 v[2:5], v[2:3], off nt
	s_nop 0
	global_load_dwordx4 v[6:9], v[6:7], off nt

; #define LAS __attribute__((address_space(3)))
; template <int MAP>
; __device__ __forceinline__ void transpose_item(const float* W, int K, int N, bf16_t* WT, int ldk, LAS float* scr, int item, int nblk, int lane) {
;     ...
; #pragma unroll
;     for (int i = 0; i < 8; ++i) { const int kk = 8 * i + (lane >> 3); f32x4 v = {0.f, 0.f, 0.f, 0.f}; if (cc < N) v = *(const f32x4*)(W + (size_t)(k0 + kk) * N + cc);
;         LAS float* d = scr + kk * 33 + 4 * (lane & 7); d[0] = v.x; d[1] = v.y; d[2] = v.z; d[3] = v.w; }
.LBB0_570:
	s_or_saveexec_b64 s[14:15], s[12:13]
	s_lshl_b32 s0, s25, 1
	v_ashrrev_i32_e32 v3, 31, v2
	s_and_b32 s12, s0, 0xffffffc0
	v_lshl_add_u64 v[26:27], v[2:3], 2, s[16:17]
	v_mov_b32_e32 v6, 0
	v_mov_b32_e32 v7, 0
	v_mov_b32_e32 v8, 0
	v_mov_b32_e32 v9, 0
	v_mov_b32_e32 v2, 0
	v_mov_b32_e32 v3, 0
	v_mov_b32_e32 v4, 0
	v_mov_b32_e32 v5, 0
	s_xor_b64 exec, exec, s[14:15]
	s_cbranch_execz .LBB0_572
	v_add_u32_e32 v2, s12, v29
	v_ashrrev_i32_e32 v3, 31, v2
	v_add_u32_e32 v6, s12, v32
	v_lshlrev_b64 v[2:3], 12, v[2:3]
	v_ashrrev_i32_e32 v7, 31, v6
	v_lshl_add_u64 v[2:3], v[26:27], 0, v[2:3]
	v_lshlrev_b64 v[6:7], 12, v[6:7]
	global_load_dwordx4 v[2:5], v[2:3], off nt
	v_lshl_add_u64 v[6:7], v[26:27], 0, v[6:7]
	global_load_dwordx4 v[6:9], v[6:7], off nt
	v_add_u32_e32 v43, v30, v31
	s_waitcnt vmcnt(0)
	ds_write2_b32 v43, v2, v3 offset1:1
	ds_write2_b32 v43, v4, v5 offset0:2 offset1:3
	v_add_u32_e32 v2, 0x420, v43
	ds_write2_b32 v2, v6, v7 offset1:1
	v_add_u32_e32 v2, 0x428, v43
	ds_write2_b32 v2, v8, v9 offset1:1
	v_add_u32_e32 v2, s12, v33
	v_add_u32_e32 v6, s12, v35
	v_ashrrev_i32_e32 v3, 31, v2
	v_ashrrev_i32_e32 v7, 31, v6
	v_lshlrev_b64 v[2:3], 12, v[2:3]
	v_lshlrev_b64 v[6:7], 12, v[6:7]
	v_lshl_add_u64 v[2:3], v[26:27], 0, v[2:3]
	v_lshl_add_u64 v[6:7], v[26:27], 0, v[6:7]
	global_load_dwordx4 v[2:5], v[2:3], off nt
	s_nop 0
	global_load_dwordx4 v[6:9], v[6:7], off nt

; #define LAS __attribute__((address_space(3)))
; template <int MAP>
; __device__ __forceinline__ void transpose_item(const float* W, int K, int N, bf16_t* WT, int ldk, LAS float* scr, int item, int nblk, int lane) {
;     ...
; #pragma unroll
;     for (int i = 0; i < 8; ++i) { const int kk = 8 * i + (lane >> 3); f32x4 v = {0.f, 0.f, 0.f, 0.f}; if (cc < N) v = *(const f32x4*)(W + (size_t)(k0 + kk) * N + cc);
;         LAS float* d = scr + kk * 33 + 4 * (lane & 7); d[0] = v.x; d[1] = v.y; d[2] = v.z; d[3] = v.w; }
.LBB0_574:
	s_or_saveexec_b64 s[14:15], s[14:15]
	v_mov_b32_e32 v6, 0
	v_mov_b32_e32 v7, 0
	v_mov_b32_e32 v8, 0
	v_mov_b32_e32 v9, 0
	v_mov_b32_e32 v2, 0
	v_mov_b32_e32 v3, 0
	v_mov_b32_e32 v4, 0
	v_mov_b32_e32 v5, 0
	s_xor_b64 exec, exec, s[14:15]
	s_cbranch_execz .LBB0_576
	v_add_u32_e32 v2, s12, v36
	v_ashrrev_i32_e32 v3, 31, v2
	v_add_u32_e32 v6, s12, v38
	v_lshlrev_b64 v[2:3], 12, v[2:3]
	v_ashrrev_i32_e32 v7, 31, v6
	v_lshl_add_u64 v[2:3], v[26:27], 0, v[2:3]
	v_lshlrev_b64 v[6:7], 12, v[6:7]
	global_load_dwordx4 v[2:5], v[2:3], off nt
	v_lshl_add_u64 v[6:7], v[26:27], 0, v[6:7]
	global_load_dwordx4 v[6:9], v[6:7], off nt
	v_add_u32_e32 v43, v30, v37
	s_waitcnt vmcnt(1)
	ds_write2_b32 v43, v2, v3 offset1:1
	ds_write2_b32 v43, v4, v5 offset0:2 offset1:3
	v_add_u32_e32 v2, 0x420, v43
	s_waitcnt vmcnt(0)
	ds_write2_b32 v2, v6, v7 offset1:1
	v_add_u32_e32 v2, 0x428, v43
	ds_write2_b32 v2, v8, v9 offset1:1
	v_add_u32_e32 v2, s12, v39
	v_add_u32_e32 v6, s12, v40
	v_ashrrev_i32_e32 v3, 31, v2
	v_ashrrev_i32_e32 v7, 31, v6
	v_lshlrev_b64 v[2:3], 12, v[2:3]
	v_lshlrev_b64 v[6:7], 12, v[6:7]
	v_lshl_add_u64 v[2:3], v[26:27], 0, v[2:3]
	v_lshl_add_u64 v[6:7], v[26:27], 0, v[6:7]
	global_load_dwordx4 v[2:5], v[2:3], off nt
	s_nop 0
	global_load_dwordx4 v[6:9], v[6:7], off nt

; #define LAS __attribute__((address_space(3)))
; template <int MAP>
; __device__ __forceinline__ void transpose_item(const float* W, int K, int N, bf16_t* WT, int ldk, LAS float* scr, int item, int nblk, int lane) {
;     ...
; #pragma unroll
;     for (int i = 0; i < 8; ++i) { const int kk = 8 * i + (lane >> 3); f32x4 v = {0.f, 0.f, 0.f, 0.f}; if (cc < N) v = *(const f32x4*)(W + (size_t)(k0 + kk) * N + cc);
;         LAS float* d = scr + kk * 33 + 4 * (lane & 7); d[0] = v.x; d[1] = v.y; d[2] = v.z; d[3] = v.w; }
.LBB0_583:
	s_or_saveexec_b64 s[14:15], s[12:13]
	s_lshl_b32 s0, s25, 4
	v_ashrrev_i32_e32 v3, 31, v2
	s_and_b32 s12, s0, 0xffffffc0
	v_lshl_add_u64 v[26:27], v[2:3], 2, s[16:17]
	v_mov_b32_e32 v6, 0
	v_mov_b32_e32 v7, 0
	v_mov_b32_e32 v8, 0
	v_mov_b32_e32 v9, 0
	v_mov_b32_e32 v2, 0
	v_mov_b32_e32 v3, 0
	v_mov_b32_e32 v4, 0
	v_mov_b32_e32 v5, 0
	s_xor_b64 exec, exec, s[14:15]
	s_cbranch_execz .LBB0_585
	v_add_u32_e32 v2, s12, v29
	v_ashrrev_i32_e32 v3, 31, v2
	v_add_u32_e32 v6, s12, v32
	v_lshlrev_b64 v[2:3], 9, v[2:3]
	v_ashrrev_i32_e32 v7, 31, v6
	v_lshl_add_u64 v[2:3], v[26:27], 0, v[2:3]
	v_lshlrev_b64 v[6:7], 9, v[6:7]
	global_load_dwordx4 v[2:5], v[2:3], off nt
	v_lshl_add_u64 v[6:7], v[26:27], 0, v[6:7]
	global_load_dwordx4 v[6:9], v[6:7], off nt
	v_add_u32_e32 v43, v30, v31
	s_waitcnt vmcnt(0)
	ds_write2_b32 v43, v2, v3 offset1:1
	ds_write2_b32 v43, v4, v5 offset0:2 offset1:3
	v_add_u32_e32 v2, 0x420, v43
	ds_write2_b32 v2, v6, v7 offset1:1
	v_add_u32_e32 v2, 0x428, v43
	ds_write2_b32 v2, v8, v9 offset1:1
	v_add_u32_e32 v2, s12, v33
	v_add_u32_e32 v6, s12, v35
	v_ashrrev_i32_e32 v3, 31, v2
	v_ashrrev_i32_e32 v7, 31, v6
	v_lshlrev_b64 v[2:3], 9, v[2:3]
	v_lshlrev_b64 v[6:7], 9, v[6:7]
	v_lshl_add_u64 v[2:3], v[26:27], 0, v[2:3]
	v_lshl_add_u64 v[6:7], v[26:27], 0, v[6:7]
	global_load_dwordx4 v[2:5], v[2:3], off nt
	s_nop 0
	global_load_dwordx4 v[6:9], v[6:7], off nt

; #define LAS __attribute__((address_space(3)))
; template <int MAP>
; __device__ __forceinline__ void transpose_item(const float* W, int K, int N, bf16_t* WT, int ldk, LAS float* scr, int item, int nblk, int lane) {
;     ...
; #pragma unroll
;     for (int i = 0; i < 8; ++i) { const int kk = 8 * i + (lane >> 3); f32x4 v = {0.f, 0.f, 0.f, 0.f}; if (cc < N) v = *(const f32x4*)(W + (size_t)(k0 + kk) * N + cc);
;         LAS float* d = scr + kk * 33 + 4 * (lane & 7); d[0] = v.x; d[1] = v.y; d[2] = v.z; d[3] = v.w; }
.LBB0_587:
	s_or_saveexec_b64 s[14:15], s[14:15]
	v_mov_b32_e32 v6, 0
	v_mov_b32_e32 v7, 0
	v_mov_b32_e32 v8, 0
	v_mov_b32_e32 v9, 0
	v_mov_b32_e32 v2, 0
	v_mov_b32_e32 v3, 0
	v_mov_b32_e32 v4, 0
	v_mov_b32_e32 v5, 0
	s_xor_b64 exec, exec, s[14:15]
	s_cbranch_execz .LBB0_589
	v_add_u32_e32 v2, s12, v36
	v_ashrrev_i32_e32 v3, 31, v2
	v_add_u32_e32 v6, s12, v38
	v_lshlrev_b64 v[2:3], 9, v[2:3]
	v_ashrrev_i32_e32 v7, 31, v6
	v_lshl_add_u64 v[2:3], v[26:27], 0, v[2:3]
	v_lshlrev_b64 v[6:7], 9, v[6:7]
	global_load_dwordx4 v[2:5], v[2:3], off nt
	v_lshl_add_u64 v[6:7], v[26:27], 0, v[6:7]
	global_load_dwordx4 v[6:9], v[6:7], off nt
	v_add_u32_e32 v43, v30, v37
	s_waitcnt vmcnt(1)
	ds_write2_b32 v43, v2, v3 offset1:1
	ds_write2_b32 v43, v4, v5 offset0:2 offset1:3
	v_add_u32_e32 v2, 0x420, v43
	s_waitcnt vmcnt(0)
	ds_write2_b32 v2, v6, v7 offset1:1
	v_add_u32_e32 v2, 0x428, v43
	ds_write2_b32 v2, v8, v9 offset1:1
	v_add_u32_e32 v2, s12, v39
	v_add_u32_e32 v6, s12, v40
	v_ashrrev_i32_e32 v3, 31, v2
	v_ashrrev_i32_e32 v7, 31, v6
	v_lshlrev_b64 v[2:3], 9, v[2:3]
	v_lshlrev_b64 v[6:7], 9, v[6:7]
	v_lshl_add_u64 v[2:3], v[26:27], 0, v[2:3]
	v_lshl_add_u64 v[6:7], v[26:27], 0, v[6:7]
	global_load_dwordx4 v[2:5], v[2:3], off nt
	s_nop 0
	global_load_dwordx4 v[6:9], v[6:7], off nt

; #define LAS __attribute__((address_space(3)))
; template <int MAP>
; __device__ __forceinline__ void transpose_item(const float* W, int K, int N, bf16_t* WT, int ldk, LAS float* scr, int item, int nblk, int lane) {
;     ...
; #pragma unroll
;     for (int i = 0; i < 8; ++i) { const int kk = 8 * i + (lane >> 3); f32x4 v = {0.f, 0.f, 0.f, 0.f}; if (cc < N) v = *(const f32x4*)(W + (size_t)(k0 + kk) * N + cc);
;         LAS float* d = scr + kk * 33 + 4 * (lane & 7); d[0] = v.x; d[1] = v.y; d[2] = v.z; d[3] = v.w; }
.LBB0_644:
	s_or_saveexec_b64 s[12:13], s[10:11]
	s_lshl_b32 s0, s17, 1
	v_ashrrev_i32_e32 v3, 31, v2
	s_and_b32 s10, s0, 0xffffffc0
	v_lshl_add_u64 v[26:27], v[2:3], 2, s[14:15]
	v_mov_b32_e32 v6, 0
	v_mov_b32_e32 v7, 0
	v_mov_b32_e32 v8, 0
	v_mov_b32_e32 v9, 0
	v_mov_b32_e32 v2, 0
	v_mov_b32_e32 v3, 0
	v_mov_b32_e32 v4, 0
	v_mov_b32_e32 v5, 0
	s_xor_b64 exec, exec, s[12:13]
	s_cbranch_execz .LBB0_646
	v_add_u32_e32 v2, s10, v29
	v_ashrrev_i32_e32 v3, 31, v2
	v_lshlrev_b64 v[2:3], 12, v[2:3]
	v_add_u32_e32 v6, s10, v32
	v_lshl_add_u64 v[2:3], v[26:27], 0, v[2:3]
	v_ashrrev_i32_e32 v7, 31, v6
	global_load_dwordx4 v[2:5], v[2:3], off nt
	v_lshlrev_b64 v[6:7], 12, v[6:7]
	v_lshl_add_u64 v[6:7], v[26:27], 0, v[6:7]
	global_load_dwordx4 v[6:9], v[6:7], off nt
	s_waitcnt vmcnt(0)
	ds_write2_b32 v43, v2, v3 offset1:1
	ds_write2_b32 v43, v4, v5 offset0:2 offset1:3
	ds_write2_b32 v44, v6, v7 offset1:1
	ds_write2_b32 v45, v8, v9 offset1:1
	v_add_u32_e32 v2, s10, v33
	v_add_u32_e32 v6, s10, v35
	v_ashrrev_i32_e32 v3, 31, v2
	v_ashrrev_i32_e32 v7, 31, v6
	v_lshlrev_b64 v[2:3], 12, v[2:3]
	v_lshlrev_b64 v[6:7], 12, v[6:7]
	v_lshl_add_u64 v[2:3], v[26:27], 0, v[2:3]
	v_lshl_add_u64 v[6:7], v[26:27], 0, v[6:7]
	global_load_dwordx4 v[2:5], v[2:3], off nt
	s_nop 0
	global_load_dwordx4 v[6:9], v[6:7], off nt

; #define LAS __attribute__((address_space(3)))
; template <int MAP>
; __device__ __forceinline__ void transpose_item(const float* W, int K, int N, bf16_t* WT, int ldk, LAS float* scr, int item, int nblk, int lane) {
;     ...
; #pragma unroll
;     for (int i = 0; i < 8; ++i) { const int kk = 8 * i + (lane >> 3); f32x4 v = {0.f, 0.f, 0.f, 0.f}; if (cc < N) v = *(const f32x4*)(W + (size_t)(k0 + kk) * N + cc);
;         LAS float* d = scr + kk * 33 + 4 * (lane & 7); d[0] = v.x; d[1] = v.y; d[2] = v.z; d[3] = v.w; }
.LBB0_648:
	s_or_saveexec_b64 s[12:13], s[12:13]
	v_mov_b32_e32 v6, 0
	v_mov_b32_e32 v7, 0
	v_mov_b32_e32 v8, 0
	v_mov_b32_e32 v9, 0
	v_mov_b32_e32 v2, 0
	v_mov_b32_e32 v3, 0
	v_mov_b32_e32 v4, 0
	v_mov_b32_e32 v5, 0
	s_xor_b64 exec, exec, s[12:13]
	s_cbranch_execz .LBB0_549
	v_add_u32_e32 v2, s10, v36
	v_ashrrev_i32_e32 v3, 31, v2
	v_lshlrev_b64 v[2:3], 12, v[2:3]
	v_add_u32_e32 v6, s10, v38
	v_lshl_add_u64 v[2:3], v[26:27], 0, v[2:3]
	v_ashrrev_i32_e32 v7, 31, v6
	global_load_dwordx4 v[2:5], v[2:3], off nt
	v_lshlrev_b64 v[6:7], 12, v[6:7]
	v_lshl_add_u64 v[6:7], v[26:27], 0, v[6:7]
	global_load_dwordx4 v[6:9], v[6:7], off nt
	s_waitcnt vmcnt(1)
	ds_write2_b32 v43, v2, v3 offset1:1
	ds_write2_b32 v43, v4, v5 offset0:2 offset1:3
	s_waitcnt vmcnt(0)
	ds_write2_b32 v44, v6, v7 offset1:1
	ds_write2_b32 v45, v8, v9 offset1:1
	v_add_u32_e32 v2, s10, v39
	v_add_u32_e32 v6, s10, v40
	v_ashrrev_i32_e32 v3, 31, v2
	v_ashrrev_i32_e32 v7, 31, v6
	v_lshlrev_b64 v[2:3], 12, v[2:3]
	v_lshlrev_b64 v[6:7], 12, v[6:7]
	v_lshl_add_u64 v[2:3], v[26:27], 0, v[2:3]
	v_lshl_add_u64 v[6:7], v[26:27], 0, v[6:7]
	global_load_dwordx4 v[2:5], v[2:3], off nt
	s_nop 0
	global_load_dwordx4 v[6:9], v[6:7], off nt
	s_branch .LBB0_549
